# v029 + mix epilogue: y0 8-byte stores merged pairwise into 16-byte stores (permlane swaps) and made write-through, so nothing is left dirty in L2 for the grid barrier to write back
# speedup vs baseline: 1.0208x; 1.0102x over previous
; #define LAS __attribute__((address_space(3)))
; __device__ __forceinline__ unsigned cvt_pk_bf16(float lo, float hi) { unsigned r; asm volatile("v_cvt_pk_bf16_f32 %0, %1, %2" : "=v"(r) : "v"(lo), "v"(hi)); return r; }
; __device__ __forceinline__ void mix_phase(const Params& p, LAS unsigned char* lds, int G, bool dry) {
;     ...
;             u32x4 w; w.x = cvt_pk_bf16(x0[0], x0[1]); w.y = cvt_pk_bf16(x0[2], x0[3]); w.z = cvt_pk_bf16(x1[0], x1[1]); w.w = cvt_pk_bf16(x1[2], x1[3]);
;             *(LAS u32x4*)(Vl + s * MIX_VP + c) = w;
;         }
;         u32x2 ur[4][4]; float bias[4];
;         bf16_t* const gup = gu + (size_t)(row_base + 64 * wr + fr) * GW + g * 256 + 64 * wc + 4 * fq;
; #pragma unroll
;         for (int m = 0; m < 4; ++m) {
;             const int tt = 64 * wr + 16 * m + fr; bias[m] = p.bsp[g * 128 + (smp ? (tt & 31) : tt)];
; #pragma unroll
;             for (int n = 0; n < 4; ++n) ur[m][n] = __builtin_nontemporal_load((const u32x2*)(gup + (size_t)m * 16 * GW + 16 * n));
;         }
;         __syncthreads();
;         f32x4 acc[4][4];
; #pragma unroll
;         for (int m = 0; m < 4; ++m)
; #pragma unroll
;             for (int n = 0; n < 4; ++n) acc[m][n] = (f32x4){0.f, 0.f, 0.f, 0.f};
; #pragma unroll
;         for (int ks = 0; ks < 4; ++ks) {
;             bf16x8 af[4], bfr[4];
; #pragma unroll
;             for (int m = 0; m < 4; ++m) af[m] = *(const LAS bf16x8*)(Wl + (64 * wr + 16 * m + fr) * MIX_WP + 32 * ks + 8 * fq);
; #pragma unroll
;             for (int n = 0; n < 4; ++n) {
;                 const LAS bf16_t* a0 = Vl + (32 * ks + 8 * fq + (fr >> 2)) * MIX_VP + 64 * wc + 16 * n + 4 * (fr & 3);
;                 const s16x4 lo = __builtin_amdgcn_ds_read_tr16_b64_v4i16((LAS s16x4*)a0), hi = __builtin_amdgcn_ds_read_tr16_b64_v4i16((LAS s16x4*)(a0 + 4 * MIX_VP));
;                 bfr[n] = (bf16x8){lo[0], lo[1], lo[2], lo[3], hi[0], hi[1], hi[2], hi[3]};
;             }
; #pragma unroll
;             for (int m = 0; m < 4; ++m)
; #pragma unroll
;                 for (int n = 0; n < 4; ++n) acc[m][n] = __builtin_amdgcn_mfma_f32_16x16x32_bf16(bfr[n], af[m], acc[m][n], 0, 0, 0);
.LBB0_214:
	v_mbcnt_lo_u32_b32 v240, -1, 0
	v_mbcnt_hi_u32_b32 v240, -1, v240
	v_lshrrev_b32_e32 v240, 4, v240
	v_lshlrev_b32_e32 v240, 3, v240
	v_mov_b32_e32 v241, 0
	v_cvt_pk_bf16_f32 v0, v0, v1
	v_cvt_pk_bf16_f32 v1, v2, v3
	v_cvt_pk_bf16_f32 v2, v4, v5
	v_cvt_pk_bf16_f32 v3, v6, v7
	ds_write_b128 v127, v[0:3] offset:34816
	v_add_u32_e32 v0, s37, v95
	v_ashrrev_i32_e32 v1, 31, v0
	v_lshlrev_b64 v[0:1], 13, v[0:1]
	v_lshl_add_u64 v[0:1], s[0:1], 0, v[0:1]
	s_lshl_b32 s18, s34, 1
	v_lshl_add_u64 v[0:1], v[0:1], 0, s[18:19]
	v_lshl_add_u64 v[0:1], v[0:1], 0, v[82:83]
	v_mov_b32_e32 v93, v83
	s_lshl_b32 s10, s36, 7
	v_lshl_add_u64 v[34:35], v[0:1], 0, v[92:93]
	v_add_u32_e32 v0, s10, v11
	v_ashrrev_i32_e32 v1, 31, v0
	v_add_u32_e32 v2, s10, v10
	v_lshl_add_u64 v[0:1], v[0:1], 2, s[76:77]
	v_ashrrev_i32_e32 v3, 31, v2
	global_load_dwordx2 v[46:47], v[34:35], off nt
	global_load_dwordx2 v[44:45], v[34:35], off offset:32 nt
	global_load_dwordx2 v[42:43], v[34:35], off offset:64 nt
	global_load_dwordx2 v[38:39], v[34:35], off offset:96 nt
	v_lshl_add_u64 v[2:3], v[2:3], 2, s[76:77]
	global_load_dword v40, v[0:1], off
	global_load_dword v28, v[2:3], off
	v_add_co_u32_e32 v22, vcc, s40, v34
	v_add_u32_e32 v0, s10, v9
	s_nop 0
	v_addc_co_u32_e32 v23, vcc, 0, v35, vcc
	global_load_dwordx2 v[36:37], v[22:23], off nt
	global_load_dwordx2 v[32:33], v[22:23], off offset:32 nt
	global_load_dwordx2 v[30:31], v[22:23], off offset:64 nt
	global_load_dwordx2 v[26:27], v[22:23], off offset:96 nt
	v_ashrrev_i32_e32 v1, 31, v0
	v_lshl_add_u64 v[0:1], v[0:1], 2, s[76:77]
	global_load_dword v16, v[0:1], off
	v_add_co_u32_e32 v10, vcc, s41, v34
	v_add_u32_e32 v0, s10, v8
	s_nop 0
	v_addc_co_u32_e32 v11, vcc, 0, v35, vcc
	global_load_dwordx2 v[24:25], v[10:11], off nt
	global_load_dwordx2 v[20:21], v[10:11], off offset:32 nt
	global_load_dwordx2 v[18:19], v[10:11], off offset:64 nt
	global_load_dwordx2 v[14:15], v[10:11], off offset:96 nt
	v_ashrrev_i32_e32 v1, 31, v0
	v_lshl_add_u64 v[0:1], v[0:1], 2, s[76:77]
	global_load_dword v4, v[0:1], off
	v_add_co_u32_e32 v0, vcc, s42, v34
	v_addc_co_u32_e32 v1, vcc, 0, v35, vcc
	global_load_dwordx2 v[12:13], v[0:1], off nt
	global_load_dwordx2 v[8:9], v[0:1], off offset:32 nt
	global_load_dwordx2 v[6:7], v[0:1], off offset:64 nt
	global_load_dwordx2 v[2:3], v[0:1], off offset:96 nt
	s_waitcnt lgkmcnt(0)
	s_barrier
	ds_read_b64_tr_b16 v[50:51], v116 offset:36928
	ds_read_b64_tr_b16 v[48:49], v116 offset:34816
	ds_read_b128 v[52:55], v128
	ds_read_b64_tr_b16 v[58:59], v116 offset:36960
	ds_read_b64_tr_b16 v[56:57], v116 offset:34848
	ds_read_b64_tr_b16 v[60:61], v116 offset:34880
	ds_read_b64_tr_b16 v[64:65], v116 offset:34912
	ds_read_b64_tr_b16 v[62:63], v116 offset:36992
	ds_read_b64_tr_b16 v[66:67], v116 offset:37024
	ds_read_b128 v[68:71], v128 offset:64
	ds_read_b128 v[136:139], v128 offset:4352
	ds_read_b128 v[140:143], v128 offset:4416
	ds_read_b128 v[156:159], v128 offset:8704
	ds_read_b128 v[160:163], v128 offset:8768
	ds_read_b128 v[176:179], v128 offset:13056
	ds_read_b128 v[180:183], v128 offset:13120
	s_waitcnt lgkmcnt(13)
	v_mfma_f32_16x16x32_bf16 v[72:75], v[48:51], v[52:55], 0
	ds_read_b64_tr_b16 v[184:185], v116 offset:51712
	ds_read_b64_tr_b16 v[186:187], v116 offset:53824
	s_waitcnt lgkmcnt(13)
	v_mfma_f32_16x16x32_bf16 v[76:79], v[56:59], v[52:55], 0
	s_waitcnt lgkmcnt(10)
	v_mfma_f32_16x16x32_bf16 v[132:135], v[60:63], v[52:55], 0
	s_waitcnt lgkmcnt(9)
	v_mfma_f32_16x16x32_bf16 v[52:55], v[64:67], v[52:55], 0
	s_waitcnt lgkmcnt(7)
	v_mfma_f32_16x16x32_bf16 v[144:147], v[48:51], v[136:139], 0
	v_mfma_f32_16x16x32_bf16 v[148:151], v[56:59], v[136:139], 0
	v_mfma_f32_16x16x32_bf16 v[152:155], v[60:63], v[136:139], 0
	v_mfma_f32_16x16x32_bf16 v[136:139], v[64:67], v[136:139], 0
	s_waitcnt lgkmcnt(5)
	v_mfma_f32_16x16x32_bf16 v[164:167], v[48:51], v[156:159], 0
	v_mfma_f32_16x16x32_bf16 v[168:171], v[56:59], v[156:159], 0
	v_mfma_f32_16x16x32_bf16 v[172:175], v[60:63], v[156:159], 0
	v_mfma_f32_16x16x32_bf16 v[156:159], v[64:67], v[156:159], 0
	s_waitcnt lgkmcnt(3)
	v_mfma_f32_16x16x32_bf16 v[48:51], v[48:51], v[176:179], 0
	v_mfma_f32_16x16x32_bf16 v[56:59], v[56:59], v[176:179], 0
	v_mfma_f32_16x16x32_bf16 v[60:63], v[60:63], v[176:179], 0
	v_mfma_f32_16x16x32_bf16 v[64:67], v[64:67], v[176:179], 0
	ds_read_b64_tr_b16 v[178:179], v116 offset:53856
	ds_read_b64_tr_b16 v[176:177], v116 offset:51744
	ds_read_b64_tr_b16 v[188:189], v116 offset:51776
	ds_read_b64_tr_b16 v[196:197], v116 offset:51808
	ds_read_b64_tr_b16 v[190:191], v116 offset:53888
	ds_read_b64_tr_b16 v[198:199], v116 offset:53920
	s_waitcnt lgkmcnt(6)
	v_mfma_f32_16x16x32_bf16 v[72:75], v[184:187], v[68:71], v[72:75]
	s_waitcnt lgkmcnt(4)
	v_mfma_f32_16x16x32_bf16 v[76:79], v[176:179], v[68:71], v[76:79]
	s_waitcnt lgkmcnt(1)
	v_mfma_f32_16x16x32_bf16 v[132:135], v[188:191], v[68:71], v[132:135]
	s_waitcnt lgkmcnt(0)
; #define LAS __attribute__((address_space(3)))
; __device__ __forceinline__ unsigned cvt_pk_bf16(float lo, float hi) { unsigned r; asm volatile("v_cvt_pk_bf16_f32 %0, %1, %2" : "=v"(r) : "v"(lo), "v"(hi)); return r; }
; __device__ __forceinline__ float bf_lo(unsigned w) { return __uint_as_float(w << 16); }
; __device__ __forceinline__ float bf_hi(unsigned w) { return __uint_as_float(w & 0xffff0000u); }
; __device__ __forceinline__ void mix_phase(const Params& p, LAS unsigned char* lds, int G, bool dry) {
;     ...
;                 const s16x4 lo = __builtin_amdgcn_ds_read_tr16_b64_v4i16((LAS s16x4*)a0), hi = __builtin_amdgcn_ds_read_tr16_b64_v4i16((LAS s16x4*)(a0 + 4 * MIX_VP));
;                 bfr[n] = (bf16x8){lo[0], lo[1], lo[2], lo[3], hi[0], hi[1], hi[2], hi[3]};
;             }
; #pragma unroll
;             for (int m = 0; m < 4; ++m)
; #pragma unroll
;                 for (int n = 0; n < 4; ++n) acc[m][n] = __builtin_amdgcn_mfma_f32_16x16x32_bf16(bfr[n], af[m], acc[m][n], 0, 0, 0);
;         }
; #pragma unroll
;         for (int m = 0; m < 4; ++m) {
; #pragma unroll
;             for (int n = 0; n < 4; ++n) {
;                 const f32x4 a = acc[m][n] + bias[m]; const u32x2 u2 = ur[m][n];
;                 u32x2 w; w.x = cvt_pk_bf16(bf_lo(u2.x) * a[0], bf_hi(u2.x) * a[1]); w.y = cvt_pk_bf16(bf_lo(u2.y) * a[2], bf_hi(u2.y) * a[3]);
;                 if (!dry) *(u32x2*)(gup + (size_t)m * 16 * GW + 16 * n) = w;
;             }
	v_mfma_f32_16x16x32_bf16 v[52:55], v[196:199], v[68:71], v[52:55]
	v_mfma_f32_16x16x32_bf16 v[68:71], v[184:187], v[140:143], v[144:147]
	v_mfma_f32_16x16x32_bf16 v[144:147], v[176:179], v[140:143], v[148:151]
	v_mfma_f32_16x16x32_bf16 v[148:151], v[188:191], v[140:143], v[152:155]
	v_mfma_f32_16x16x32_bf16 v[136:139], v[196:199], v[140:143], v[136:139]
	v_mfma_f32_16x16x32_bf16 v[140:143], v[184:187], v[160:163], v[164:167]
	v_mfma_f32_16x16x32_bf16 v[152:155], v[176:179], v[160:163], v[168:171]
	v_mfma_f32_16x16x32_bf16 v[164:167], v[188:191], v[160:163], v[172:175]
	v_mfma_f32_16x16x32_bf16 v[156:159], v[196:199], v[160:163], v[156:159]
	ds_read_b128 v[160:163], v128 offset:128
	ds_read_b64_tr_b16 v[170:171], v117 offset:35904
	v_mfma_f32_16x16x32_bf16 v[48:51], v[184:187], v[180:183], v[48:51]
	v_mfma_f32_16x16x32_bf16 v[56:59], v[176:179], v[180:183], v[56:59]
	ds_read_b64_tr_b16 v[168:169], v117 offset:33792
	ds_read_b64_tr_b16 v[172:173], v117 offset:33824
	ds_read_b64_tr_b16 v[176:177], v117 offset:33856
	ds_read_b64_tr_b16 v[184:185], v117 offset:33888
	v_mfma_f32_16x16x32_bf16 v[60:63], v[188:191], v[180:183], v[60:63]
	v_mfma_f32_16x16x32_bf16 v[64:67], v[196:199], v[180:183], v[64:67]
	ds_read_b64_tr_b16 v[174:175], v117 offset:35936
	ds_read_b64_tr_b16 v[178:179], v117 offset:35968
	ds_read_b64_tr_b16 v[186:187], v117 offset:36000
	ds_read_b128 v[180:183], v128 offset:192
	ds_read_b128 v[188:191], v128 offset:4480
	ds_read_b128 v[196:199], v128 offset:4544
	ds_read_b128 v[200:203], v128 offset:8832
	ds_read_b128 v[204:207], v128 offset:8896
	ds_read_b128 v[208:211], v128 offset:13184
	ds_read_b128 v[212:215], v128 offset:13248
	ds_read_b64_tr_b16 v[216:217], v117 offset:50688
	ds_read_b64_tr_b16 v[218:219], v117 offset:52800
	s_waitcnt lgkmcnt(14)
	v_mfma_f32_16x16x32_bf16 v[72:75], v[168:171], v[160:163], v[72:75]
	ds_read_b64_tr_b16 v[220:221], v117 offset:50720
	ds_read_b64_tr_b16 v[224:225], v117 offset:50752
	ds_read_b64_tr_b16 v[228:229], v117 offset:50784
	ds_read_b64_tr_b16 v[222:223], v117 offset:52832
	ds_read_b64_tr_b16 v[226:227], v117 offset:52864
	ds_read_b64_tr_b16 v[230:231], v117 offset:52896
	s_waitcnt lgkmcnt(14)
	v_mfma_f32_16x16x32_bf16 v[76:79], v[172:175], v[160:163], v[76:79]
	s_waitcnt lgkmcnt(6)
	v_mfma_f32_16x16x32_bf16 v[72:75], v[216:219], v[180:183], v[72:75]
	s_waitcnt lgkmcnt(2)
	v_mfma_f32_16x16x32_bf16 v[76:79], v[220:223], v[180:183], v[76:79]
	v_mfma_f32_16x16x32_bf16 v[132:135], v[176:179], v[160:163], v[132:135]
	s_waitcnt vmcnt(15)
	v_lshlrev_b32_e32 v5, 16, v46
	v_and_b32_e32 v17, 0xffff0000, v46
	s_nop 3
	v_pk_add_f32 v[72:73], v[40:41], v[72:73] op_sel_hi:[0,1]
	v_mul_f32_e32 v5, v72, v5
	v_mul_f32_e32 v17, v73, v17
	v_mfma_f32_16x16x32_bf16 v[52:55], v[184:187], v[160:163], v[52:55]
	v_add_f32_e64 v160, v40, v74
	v_add_f32_e64 v161, v40, v75
	v_cvt_pk_bf16_f32 v46, v5, v17
	v_lshlrev_b32_e32 v5, 16, v47
	v_and_b32_e32 v17, 0xffff0000, v47
	v_mul_f32_e32 v5, v160, v5
	v_mul_f32_e32 v17, v161, v17
	v_mfma_f32_16x16x32_bf16 v[72:75], v[172:175], v[188:191], v[144:147]
	v_cvt_pk_bf16_f32 v47, v5, v17
	v_lshlrev_b32_e32 v5, 16, v44
	v_and_b32_e32 v17, 0xffff0000, v44
	v_mfma_f32_16x16x32_bf16 v[144:147], v[176:179], v[188:191], v[148:151]
	v_mov_b32_e32 v236, v46
	v_mov_b32_e32 v237, v47
	v_pk_add_f32 v[46:47], v[40:41], v[78:79] op_sel_hi:[0,1]
	s_nop 0
	v_pk_add_f32 v[148:149], v[40:41], v[76:77] op_sel_hi:[0,1]
	v_mul_f32_e32 v5, v148, v5
	v_mul_f32_e32 v17, v149, v17
	v_cvt_pk_bf16_f32 v148, v5, v17
	v_lshlrev_b32_e32 v5, 16, v45
	v_and_b32_e32 v17, 0xffff0000, v45
	v_mul_f32_e32 v5, v46, v5
	v_mul_f32_e32 v17, v47, v17
	s_waitcnt lgkmcnt(1)
	v_mfma_f32_16x16x32_bf16 v[44:47], v[224:227], v[180:183], v[132:135]
	v_cvt_pk_bf16_f32 v149, v5, v17
	v_lshlrev_b32_e32 v5, 16, v42
	v_and_b32_e32 v17, 0xffff0000, v42
	v_mfma_f32_16x16x32_bf16 v[68:71], v[168:171], v[188:191], v[68:71]
	v_mov_b32_e32 v238, v148
	v_mov_b32_e32 v239, v149
	s_nop 1
	v_permlane32_swap_b32_e32 v236, v238
	v_permlane32_swap_b32_e32 v237, v239
	s_nop 1
	v_permlane16_swap_b32_e32 v236, v238
	v_permlane16_swap_b32_e32 v237, v239
	v_lshl_add_u64 v[242:243], v[34:35], 0, v[240:241]
	global_store_dwordx4 v[242:243], v[236:239], off sc1
	s_nop 1
	s_nop 3
	v_pk_add_f32 v[150:151], v[40:41], v[44:45] op_sel_hi:[0,1]
	v_mul_f32_e32 v5, v150, v5
	s_waitcnt lgkmcnt(0)
	v_mfma_f32_16x16x32_bf16 v[52:55], v[228:231], v[180:183], v[52:55]
	v_mul_f32_e32 v17, v151, v17
	v_pk_add_f32 v[148:149], v[40:41], v[46:47] op_sel_hi:[0,1]
	v_cvt_pk_bf16_f32 v42, v5, v17
	v_lshlrev_b32_e32 v5, 16, v43
	v_and_b32_e32 v17, 0xffff0000, v43
	v_mul_f32_e32 v5, v148, v5
	v_mul_f32_e32 v17, v149, v17
	v_cvt_pk_bf16_f32 v43, v5, v17
	v_mov_b32_e32 v236, v42
	v_mov_b32_e32 v237, v43
	s_nop 0
	v_pk_add_f32 v[148:149], v[40:41], v[54:55] op_sel_hi:[0,1]
	v_pk_add_f32 v[52:53], v[40:41], v[52:53] op_sel_hi:[0,1]
	v_lshlrev_b32_e32 v5, 16, v38
	v_mfma_f32_16x16x32_bf16 v[40:43], v[176:179], v[208:211], v[60:63]
	v_and_b32_e32 v17, 0xffff0000, v38
	v_mul_f32_e32 v5, v52, v5
	v_mul_f32_e32 v17, v53, v17
	v_mfma_f32_16x16x32_bf16 v[60:63], v[216:219], v[196:199], v[68:71]
	v_cvt_pk_bf16_f32 v38, v5, v17
	v_lshlrev_b32_e32 v5, 16, v39
	v_and_b32_e32 v17, 0xffff0000, v39
	v_mul_f32_e32 v5, v148, v5
	v_mul_f32_e32 v17, v149, v17
	v_cvt_pk_bf16_f32 v39, v5, v17
	v_mfma_f32_16x16x32_bf16 v[52:55], v[184:187], v[208:211], v[64:67]
	v_mov_b32_e32 v238, v38
	v_mov_b32_e32 v239, v39
	s_nop 1
	v_permlane32_swap_b32_e32 v236, v238
	v_permlane32_swap_b32_e32 v237, v239
	s_nop 1
	v_permlane16_swap_b32_e32 v236, v238
	v_permlane16_swap_b32_e32 v237, v239
	v_lshl_add_u64 v[242:243], v[34:35], 0, v[240:241]
	global_store_dwordx4 v[242:243], v[236:239], off offset:64 sc1
	s_nop 1
	s_waitcnt vmcnt(16)
; __device__ __forceinline__ unsigned cvt_pk_bf16(float lo, float hi) { unsigned r; asm volatile("v_cvt_pk_bf16_f32 %0, %1, %2" : "=v"(r) : "v"(lo), "v"(hi)); return r; }
; __device__ __forceinline__ float bf_lo(unsigned w) { return __uint_as_float(w << 16); }
; __device__ __forceinline__ float bf_hi(unsigned w) { return __uint_as_float(w & 0xffff0000u); }
; __device__ __forceinline__ void mix_phase(const Params& p, LAS unsigned char* lds, int G, bool dry) {
;     ...
;         for (int m = 0; m < 4; ++m) {
; #pragma unroll
;             for (int n = 0; n < 4; ++n) {
;                 const f32x4 a = acc[m][n] + bias[m]; const u32x2 u2 = ur[m][n];
;                 u32x2 w; w.x = cvt_pk_bf16(bf_lo(u2.x) * a[0], bf_hi(u2.x) * a[1]); w.y = cvt_pk_bf16(bf_lo(u2.y) * a[2], bf_hi(u2.y) * a[3]);
;                 if (!dry) *(u32x2*)(gup + (size_t)m * 16 * GW + 16 * n) = w;
;             }
	s_nop 0
	v_pk_add_f32 v[38:39], v[28:29], v[60:61] op_sel_hi:[0,1]
	s_waitcnt vmcnt(15)
	v_lshlrev_b32_e32 v5, 16, v36
	v_mfma_f32_16x16x32_bf16 v[64:67], v[220:223], v[196:199], v[72:75]
	v_and_b32_e32 v17, 0xffff0000, v36
	v_mul_f32_e32 v5, v38, v5
	v_mul_f32_e32 v17, v39, v17
	v_pk_add_f32 v[34:35], v[28:29], v[62:63] op_sel_hi:[0,1]
	v_cvt_pk_bf16_f32 v38, v5, v17
	v_lshlrev_b32_e32 v5, 16, v37
	v_and_b32_e32 v17, 0xffff0000, v37
	v_mul_f32_e32 v5, v34, v5
	v_mul_f32_e32 v17, v35, v17
	v_mfma_f32_16x16x32_bf16 v[76:79], v[184:187], v[188:191], v[136:139]
	v_cvt_pk_bf16_f32 v39, v5, v17
	v_add_f32_e64 v64, v28, v64
	v_add_f32_e64 v65, v28, v65
	s_waitcnt vmcnt(14)
	v_lshlrev_b32_e32 v5, 16, v32
	v_mfma_f32_16x16x32_bf16 v[60:63], v[224:227], v[196:199], v[144:147]
	v_and_b32_e32 v17, 0xffff0000, v32
	v_mul_f32_e32 v5, v64, v5
	v_mul_f32_e32 v17, v65, v17
	v_mov_b32_e32 v236, v38
	v_mov_b32_e32 v237, v39
	v_pk_add_f32 v[38:39], v[28:29], v[66:67] op_sel_hi:[0,1]
	v_cvt_pk_bf16_f32 v32, v5, v17
	v_lshlrev_b32_e32 v5, 16, v33
	v_and_b32_e32 v17, 0xffff0000, v33
	v_mul_f32_e32 v5, v38, v5
	v_mul_f32_e32 v17, v39, v17
	v_mfma_f32_16x16x32_bf16 v[136:139], v[168:171], v[200:203], v[140:143]
	v_cvt_pk_bf16_f32 v33, v5, v17
	s_waitcnt vmcnt(13)
	v_lshlrev_b32_e32 v5, 16, v30
	v_and_b32_e32 v17, 0xffff0000, v30
	v_mfma_f32_16x16x32_bf16 v[68:71], v[228:231], v[196:199], v[76:79]
	v_mov_b32_e32 v238, v32
	v_mov_b32_e32 v239, v33
	s_nop 1
	v_permlane32_swap_b32_e32 v236, v238
	v_permlane32_swap_b32_e32 v237, v239
	s_nop 1
	v_permlane16_swap_b32_e32 v236, v238
	v_permlane16_swap_b32_e32 v237, v239
	v_lshl_add_u64 v[242:243], v[22:23], 0, v[240:241]
	global_store_dwordx4 v[242:243], v[236:239], off sc1
	s_nop 1
	v_pk_add_f32 v[32:33], v[28:29], v[62:63] op_sel_hi:[0,1]
	v_mfma_f32_16x16x32_bf16 v[38:41], v[224:227], v[212:215], v[40:43]
	s_nop 2
	v_add_f32_e64 v42, v28, v60
	v_add_f32_e64 v43, v28, v61
	v_mul_f32_e32 v5, v42, v5
	v_mul_f32_e32 v17, v43, v17
	v_cvt_pk_bf16_f32 v30, v5, v17
	v_lshlrev_b32_e32 v5, 16, v31
	v_and_b32_e32 v17, 0xffff0000, v31
	v_mul_f32_e32 v5, v32, v5
	v_mul_f32_e32 v17, v33, v17
	v_cvt_pk_bf16_f32 v31, v5, v17
	v_mfma_f32_16x16x32_bf16 v[140:143], v[172:175], v[200:203], v[152:155]
	v_mov_b32_e32 v236, v30
	v_mov_b32_e32 v237, v31
	v_pk_add_f32 v[30:31], v[28:29], v[70:71] op_sel_hi:[0,1]
	v_pk_add_f32 v[28:29], v[28:29], v[68:69] op_sel_hi:[0,1]
	v_mfma_f32_16x16x32_bf16 v[72:75], v[216:219], v[204:207], v[136:139]
	s_waitcnt vmcnt(13)
	v_lshlrev_b32_e32 v5, 16, v26
	v_and_b32_e32 v17, 0xffff0000, v26
	v_mul_f32_e32 v5, v28, v5
	v_mul_f32_e32 v17, v29, v17
	v_cvt_pk_bf16_f32 v26, v5, v17
	v_lshlrev_b32_e32 v5, 16, v27
	v_and_b32_e32 v17, 0xffff0000, v27
	v_mul_f32_e32 v5, v30, v5
	v_mul_f32_e32 v17, v31, v17
	v_cvt_pk_bf16_f32 v27, v5, v17
	v_mfma_f32_16x16x32_bf16 v[132:135], v[176:179], v[200:203], v[164:167]
	v_mov_b32_e32 v238, v26
	v_mov_b32_e32 v239, v27
	s_nop 1
	v_permlane32_swap_b32_e32 v236, v238
	v_permlane32_swap_b32_e32 v237, v239
	s_nop 1
	v_permlane16_swap_b32_e32 v236, v238
	v_permlane16_swap_b32_e32 v237, v239
	v_lshl_add_u64 v[242:243], v[22:23], 0, v[240:241]
	global_store_dwordx4 v[242:243], v[236:239], off offset:64 sc1
	s_nop 1
	s_waitcnt vmcnt(13)
	v_pk_add_f32 v[22:23], v[16:17], v[74:75] op_sel_hi:[0,1]
	v_pk_add_f32 v[26:27], v[16:17], v[72:73] op_sel_hi:[0,1]
	v_mfma_f32_16x16x32_bf16 v[34:37], v[220:223], v[204:207], v[140:143]
	s_waitcnt vmcnt(12)
	v_lshlrev_b32_e32 v5, 16, v24
	v_and_b32_e32 v17, 0xffff0000, v24
	v_mul_f32_e32 v5, v26, v5
	v_mul_f32_e32 v17, v27, v17
	v_cvt_pk_bf16_f32 v24, v5, v17
	v_lshlrev_b32_e32 v5, 16, v25
	v_and_b32_e32 v17, 0xffff0000, v25
	v_mul_f32_e32 v5, v22, v5
	v_mul_f32_e32 v17, v23, v17
	v_cvt_pk_bf16_f32 v25, v5, v17
	v_mfma_f32_16x16x32_bf16 v[44:47], v[184:187], v[200:203], v[156:159]
	v_mov_b32_e32 v236, v24
	v_mov_b32_e32 v237, v25
	v_pk_add_f32 v[22:23], v[16:17], v[36:37] op_sel_hi:[0,1]
	v_pk_add_f32 v[24:25], v[16:17], v[34:35] op_sel_hi:[0,1]
	v_mfma_f32_16x16x32_bf16 v[76:79], v[224:227], v[204:207], v[132:135]
	s_waitcnt vmcnt(11)
	v_lshlrev_b32_e32 v5, 16, v20
	v_and_b32_e32 v17, 0xffff0000, v20
	v_mul_f32_e32 v5, v24, v5
	v_mul_f32_e32 v17, v25, v17
	v_cvt_pk_bf16_f32 v20, v5, v17
	v_lshlrev_b32_e32 v5, 16, v21
	v_and_b32_e32 v17, 0xffff0000, v21
	v_mul_f32_e32 v5, v22, v5
	v_mul_f32_e32 v17, v23, v17
	v_cvt_pk_bf16_f32 v21, v5, v17
	v_mfma_f32_16x16x32_bf16 v[44:47], v[228:231], v[204:207], v[44:47]
	v_mov_b32_e32 v238, v20
	v_mov_b32_e32 v239, v21
	s_nop 1
	v_permlane32_swap_b32_e32 v236, v238
	v_permlane32_swap_b32_e32 v237, v239
	s_nop 1
	v_permlane16_swap_b32_e32 v236, v238
	v_permlane16_swap_b32_e32 v237, v239
	v_lshl_add_u64 v[242:243], v[10:11], 0, v[240:241]
	global_store_dwordx4 v[242:243], v[236:239], off sc1
	s_nop 1
	v_pk_add_f32 v[20:21], v[16:17], v[78:79] op_sel_hi:[0,1]
	v_pk_add_f32 v[22:23], v[16:17], v[76:77] op_sel_hi:[0,1]
	s_waitcnt vmcnt(11)
; __device__ __forceinline__ unsigned cvt_pk_bf16(float lo, float hi) { unsigned r; asm volatile("v_cvt_pk_bf16_f32 %0, %1, %2" : "=v"(r) : "v"(lo), "v"(hi)); return r; }
; __device__ __forceinline__ float bf_lo(unsigned w) { return __uint_as_float(w << 16); }
; __device__ __forceinline__ float bf_hi(unsigned w) { return __uint_as_float(w & 0xffff0000u); }
; __device__ __forceinline__ void mix_phase(const Params& p, LAS unsigned char* lds, int G, bool dry) {
;     ...
;         for (int m = 0; m < 4; ++m) {
; #pragma unroll
;             for (int n = 0; n < 4; ++n) {
;                 const f32x4 a = acc[m][n] + bias[m]; const u32x2 u2 = ur[m][n];
;                 u32x2 w; w.x = cvt_pk_bf16(bf_lo(u2.x) * a[0], bf_hi(u2.x) * a[1]); w.y = cvt_pk_bf16(bf_lo(u2.y) * a[2], bf_hi(u2.y) * a[3]);
;                 if (!dry) *(u32x2*)(gup + (size_t)m * 16 * GW + 16 * n) = w;
;             }
;         }
;         if (tid == 0) misc[0] = nticket;
	v_lshlrev_b32_e32 v5, 16, v18
	v_and_b32_e32 v17, 0xffff0000, v18
	v_mfma_f32_16x16x32_bf16 v[48:51], v[168:171], v[208:211], v[48:51]
	v_mul_f32_e32 v5, v22, v5
	v_mul_f32_e32 v17, v23, v17
	v_cvt_pk_bf16_f32 v18, v5, v17
	v_lshlrev_b32_e32 v5, 16, v19
	v_and_b32_e32 v17, 0xffff0000, v19
	v_mul_f32_e32 v5, v20, v5
	v_mul_f32_e32 v17, v21, v17
	v_cvt_pk_bf16_f32 v19, v5, v17
	v_mov_b32_e32 v236, v18
	v_mov_b32_e32 v237, v19
	v_pk_add_f32 v[18:19], v[16:17], v[46:47] op_sel_hi:[0,1]
	v_pk_add_f32 v[16:17], v[16:17], v[44:45] op_sel_hi:[0,1]
	s_waitcnt vmcnt(10)
	v_lshlrev_b32_e32 v5, 16, v14
	v_and_b32_e32 v14, 0xffff0000, v14
	v_mfma_f32_16x16x32_bf16 v[48:51], v[216:219], v[212:215], v[48:51]
	v_mul_f32_e32 v5, v16, v5
	v_mul_f32_e32 v14, v17, v14
	v_cvt_pk_bf16_f32 v14, v5, v14
	v_mfma_f32_16x16x32_bf16 v[56:59], v[172:175], v[208:211], v[56:59]
	v_lshlrev_b32_e32 v5, 16, v15
	v_and_b32_e32 v15, 0xffff0000, v15
	v_mul_f32_e32 v15, v19, v15
	v_mul_f32_e32 v5, v18, v5
	v_cvt_pk_bf16_f32 v15, v5, v15
	v_mov_b32_e32 v238, v14
	v_mov_b32_e32 v239, v15
	s_nop 1
	v_permlane32_swap_b32_e32 v236, v238
	v_permlane32_swap_b32_e32 v237, v239
	s_nop 1
	v_permlane16_swap_b32_e32 v236, v238
	v_permlane16_swap_b32_e32 v237, v239
	v_lshl_add_u64 v[242:243], v[10:11], 0, v[240:241]
	global_store_dwordx4 v[242:243], v[236:239], off offset:64 sc1
	s_nop 1
	s_waitcnt vmcnt(10)
	v_pk_add_f32 v[10:11], v[4:5], v[50:51] op_sel_hi:[0,1]
	v_pk_add_f32 v[14:15], v[4:5], v[48:49] op_sel_hi:[0,1]
	s_waitcnt vmcnt(9)
	v_lshlrev_b32_e32 v5, 16, v12
	v_and_b32_e32 v12, 0xffff0000, v12
	v_mfma_f32_16x16x32_bf16 v[56:59], v[220:223], v[212:215], v[56:59]
	v_mul_f32_e32 v5, v14, v5
	v_mul_f32_e32 v12, v15, v12
	v_cvt_pk_bf16_f32 v12, v5, v12
	v_lshlrev_b32_e32 v5, 16, v13
	v_mul_f32_e32 v5, v10, v5
	v_and_b32_e32 v10, 0xffff0000, v13
	v_mul_f32_e32 v10, v11, v10
	v_cvt_pk_bf16_f32 v13, v5, v10
	v_mov_b32_e32 v236, v12
	v_mov_b32_e32 v237, v13
	s_nop 0
	v_pk_add_f32 v[10:11], v[4:5], v[58:59] op_sel_hi:[0,1]
	v_pk_add_f32 v[12:13], v[4:5], v[56:57] op_sel_hi:[0,1]
	s_waitcnt vmcnt(8)
	v_lshlrev_b32_e32 v5, 16, v8
	v_and_b32_e32 v8, 0xffff0000, v8
	v_mul_f32_e32 v5, v12, v5
	v_mul_f32_e32 v8, v13, v8
	v_cvt_pk_bf16_f32 v8, v5, v8
	v_lshlrev_b32_e32 v5, 16, v9
	v_and_b32_e32 v9, 0xffff0000, v9
	v_mul_f32_e32 v9, v11, v9
	v_mul_f32_e32 v5, v10, v5
	v_cvt_pk_bf16_f32 v9, v5, v9
	v_mov_b32_e32 v238, v8
	v_mov_b32_e32 v239, v9
	s_nop 1
	v_permlane32_swap_b32_e32 v236, v238
	v_permlane32_swap_b32_e32 v237, v239
	s_nop 1
	v_permlane16_swap_b32_e32 v236, v238
	v_permlane16_swap_b32_e32 v237, v239
	v_lshl_add_u64 v[242:243], v[0:1], 0, v[240:241]
	global_store_dwordx4 v[242:243], v[236:239], off sc1
	s_nop 1
	v_pk_add_f32 v[8:9], v[4:5], v[40:41] op_sel_hi:[0,1]
	v_pk_add_f32 v[10:11], v[4:5], v[38:39] op_sel_hi:[0,1]
	s_waitcnt vmcnt(8)
	v_lshlrev_b32_e32 v5, 16, v6
	v_and_b32_e32 v6, 0xffff0000, v6
	v_mfma_f32_16x16x32_bf16 v[52:55], v[228:231], v[212:215], v[52:55]
	v_mul_f32_e32 v5, v10, v5
	v_mul_f32_e32 v6, v11, v6
	v_cvt_pk_bf16_f32 v6, v5, v6
	v_lshlrev_b32_e32 v5, 16, v7
	v_and_b32_e32 v7, 0xffff0000, v7
	v_mul_f32_e32 v7, v9, v7
	v_mul_f32_e32 v5, v8, v5
	v_cvt_pk_bf16_f32 v7, v5, v7
	v_mov_b32_e32 v236, v6
	v_mov_b32_e32 v237, v7
	s_nop 0
	v_pk_add_f32 v[6:7], v[4:5], v[54:55] op_sel_hi:[0,1]
	v_pk_add_f32 v[4:5], v[4:5], v[52:53] op_sel_hi:[0,1]
	s_waitcnt vmcnt(7)
	v_lshlrev_b32_e32 v8, 16, v2
	v_and_b32_e32 v2, 0xffff0000, v2
	v_mul_f32_e32 v4, v4, v8
	v_mul_f32_e32 v2, v5, v2
	v_cvt_pk_bf16_f32 v2, v4, v2
	v_lshlrev_b32_e32 v4, 16, v3
	v_and_b32_e32 v3, 0xffff0000, v3
	v_mul_f32_e32 v3, v7, v3
	v_mul_f32_e32 v4, v6, v4
	v_cvt_pk_bf16_f32 v3, v4, v3
	v_mov_b32_e32 v238, v2
	v_mov_b32_e32 v239, v3
	s_nop 1
	v_permlane32_swap_b32_e32 v236, v238
	v_permlane32_swap_b32_e32 v237, v239
	s_nop 1
	v_permlane16_swap_b32_e32 v236, v238
	v_permlane16_swap_b32_e32 v237, v239
	v_lshl_add_u64 v[242:243], v[0:1], 0, v[240:241]
	global_store_dwordx4 v[242:243], v[236:239], off offset:64 sc1
	s_nop 1
	s_and_saveexec_b64 s[10:11], s[12:13]
	s_xor_b64 s[10:11], exec, s[10:11]
	s_cbranch_execz .LBB0_157
	v_mov_b32_e32 v0, s33
	ds_write_b32 v0, v235
	s_branch .LBB0_157
